# P5 sample-row GEMM: weight tile staged once per workgroup through LDS-DMA, activation fragments all in flight
# speedup vs baseline: 1.0106x; 1.0084x over previous
; __device__ __forceinline__ f32x4 mfma16(h16x8 a, h16x8 b, f32x4 c) { return __builtin_amdgcn_mfma_f32_16x16x32_f16(a, b, c, 0, 0, 0); }
; template <int MODE>
; __device__ __forceinline__ void skinny(const Params& p, const h16* A, int lda, int row0, int nrt, const h16* Bt, int K, int nct) {
;     ...
;     for (int task = gw; task < nrt * nct; task += ngw) {
;         const int rt = task % nrt, ct = task / nrt;
;         const h16* ap = A + (size_t)(row0 + rt * 16 + fr) * lda + fq * 8;
;         const h16* bp = Bt + (size_t)(ct * 16 + fr) * K + fq * 8;
;         f32x4 acc = {0.f, 0.f, 0.f, 0.f};
; #pragma unroll 8
;         for (int k = 0; k < K; k += 32) { const h16x8 a = *(const h16x8*)(ap + k); const h16x8 b = *(const h16x8*)(bp + k); acc = mfma16(b, a, acc); }
.LBB0_491:
	s_cmpk_lg_i32 s33, 0x100
	s_cbranch_scc1 .Lsk5_orig
	v_lshrrev_b32_e32 v24, 6, v132
	v_and_b32_e32 v200, 63, v132
	v_readfirstlane_b32 s97, v24
	v_lshlrev_b32_e32 v200, 4, v200
	v_lshl_add_u64 v[24:25], v[8:9], 0, v[140:141]
	v_lshl_add_u64 v[26:27], v[6:7], 0, v[140:141]
	s_lshl_b32 s98, s97, 8
	s_lshl_b32 s99, s97, 12
	s_add_u32 s98, s98, 0x988000
	v_add_co_u32_e32 v24, vcc, s98, v24
	s_nop 1
	v_addc_co_u32_e32 v25, vcc, 0, v25, vcc
	v_add_co_u32_e32 v26, vcc, 0x5c72900, v26
	s_nop 1
	v_addc_co_u32_e32 v27, vcc, 0, v27, vcc
	s_add_i32 m0, s99, 0x0
	s_nop 0
	global_load_lds_dwordx4 v[24:25], off
	v_add_co_u32_e32 v24, vcc, 64, v24
	s_nop 1
	v_addc_co_u32_e32 v25, vcc, 0, v25, vcc
	s_add_i32 m0, s99, 0x400
	s_nop 0
	global_load_lds_dwordx4 v[24:25], off
	v_add_co_u32_e32 v24, vcc, 64, v24
	s_nop 1
	v_addc_co_u32_e32 v25, vcc, 0, v25, vcc
	s_add_i32 m0, s99, 0x800
	s_nop 0
	global_load_lds_dwordx4 v[24:25], off
	v_add_co_u32_e32 v24, vcc, 64, v24
	s_nop 1
	v_addc_co_u32_e32 v25, vcc, 0, v25, vcc
	s_add_i32 m0, s99, 0xc00
	s_nop 0
	global_load_lds_dwordx4 v[24:25], off
	global_load_dwordx4 v[28:31], v[26:27], off
	global_load_dwordx4 v[32:35], v[26:27], off offset:64
	global_load_dwordx4 v[36:39], v[26:27], off offset:128
	global_load_dwordx4 v[40:43], v[26:27], off offset:192
	global_load_dwordx4 v[44:47], v[26:27], off offset:256
	global_load_dwordx4 v[48:51], v[26:27], off offset:320
	global_load_dwordx4 v[52:55], v[26:27], off offset:384
	global_load_dwordx4 v[56:59], v[26:27], off offset:448
	global_load_dwordx4 v[60:63], v[26:27], off offset:512
	global_load_dwordx4 v[64:67], v[26:27], off offset:576
	global_load_dwordx4 v[68:71], v[26:27], off offset:640
	global_load_dwordx4 v[72:75], v[26:27], off offset:704
	global_load_dwordx4 v[76:79], v[26:27], off offset:768
	global_load_dwordx4 v[80:83], v[26:27], off offset:832
	global_load_dwordx4 v[84:87], v[26:27], off offset:896
	global_load_dwordx4 v[88:91], v[26:27], off offset:960
	global_load_dwordx4 v[92:95], v[26:27], off offset:1024
	global_load_dwordx4 v[96:99], v[26:27], off offset:1088
	global_load_dwordx4 v[100:103], v[26:27], off offset:1152
	global_load_dwordx4 v[104:107], v[26:27], off offset:1216
	global_load_dwordx4 v[108:111], v[26:27], off offset:1280
	global_load_dwordx4 v[112:115], v[26:27], off offset:1344
	global_load_dwordx4 v[116:119], v[26:27], off offset:1408
	global_load_dwordx4 v[120:123], v[26:27], off offset:1472
	global_load_dwordx4 v[124:127], v[26:27], off offset:1536
	global_load_dwordx4 v[148:151], v[26:27], off offset:1600
	global_load_dwordx4 v[152:155], v[26:27], off offset:1664
	global_load_dwordx4 v[156:159], v[26:27], off offset:1728
	global_load_dwordx4 v[160:163], v[26:27], off offset:1792
	global_load_dwordx4 v[164:167], v[26:27], off offset:1856
	global_load_dwordx4 v[168:171], v[26:27], off offset:1920
	global_load_dwordx4 v[172:175], v[26:27], off offset:1984
	s_waitcnt vmcnt(32)
	s_barrier
; __device__ __forceinline__ f32x4 mfma16(h16x8 a, h16x8 b, f32x4 c) { return __builtin_amdgcn_mfma_f32_16x16x32_f16(a, b, c, 0, 0, 0); }
; template <int MODE>
; __device__ __forceinline__ void skinny(const Params& p, const h16* A, int lda, int row0, int nrt, const h16* Bt, int K, int nct) {
;     ...
;         for (int k = 0; k < K; k += 32) { const h16x8 a = *(const h16x8*)(ap + k); const h16x8 b = *(const h16x8*)(bp + k); acc = mfma16(b, a, acc); }
	ds_read_b128 v[176:179], v200
	ds_read_b128 v[180:183], v200 offset:1024
	ds_read_b128 v[184:187], v200 offset:2048
	ds_read_b128 v[188:191], v200 offset:3072
	s_waitcnt vmcnt(31) lgkmcnt(3)
	v_mfma_f32_16x16x32_f16 v[0:3], v[176:179], v[28:31], v[0:3]
	ds_read_b128 v[192:195], v200 offset:4096
	s_waitcnt vmcnt(30) lgkmcnt(3)
	v_mfma_f32_16x16x32_f16 v[0:3], v[180:183], v[32:35], v[0:3]
	ds_read_b128 v[196:199], v200 offset:5120
	s_waitcnt vmcnt(29) lgkmcnt(3)
	v_mfma_f32_16x16x32_f16 v[0:3], v[184:187], v[36:39], v[0:3]
	ds_read_b128 v[176:179], v200 offset:6144
	s_waitcnt vmcnt(28) lgkmcnt(3)
	v_mfma_f32_16x16x32_f16 v[0:3], v[188:191], v[40:43], v[0:3]
	ds_read_b128 v[180:183], v200 offset:7168
	s_waitcnt vmcnt(27) lgkmcnt(3)
	v_mfma_f32_16x16x32_f16 v[0:3], v[192:195], v[44:47], v[0:3]
	ds_read_b128 v[184:187], v200 offset:8192
	s_waitcnt vmcnt(26) lgkmcnt(3)
	v_mfma_f32_16x16x32_f16 v[0:3], v[196:199], v[48:51], v[0:3]
	ds_read_b128 v[188:191], v200 offset:9216
	s_waitcnt vmcnt(25) lgkmcnt(3)
	v_mfma_f32_16x16x32_f16 v[0:3], v[176:179], v[52:55], v[0:3]
	ds_read_b128 v[192:195], v200 offset:10240
	s_waitcnt vmcnt(24) lgkmcnt(3)
	v_mfma_f32_16x16x32_f16 v[0:3], v[180:183], v[56:59], v[0:3]
	ds_read_b128 v[196:199], v200 offset:11264
	s_waitcnt vmcnt(23) lgkmcnt(3)
	v_mfma_f32_16x16x32_f16 v[0:3], v[184:187], v[60:63], v[0:3]
	ds_read_b128 v[176:179], v200 offset:12288
	s_waitcnt vmcnt(22) lgkmcnt(3)
	v_mfma_f32_16x16x32_f16 v[0:3], v[188:191], v[64:67], v[0:3]
	ds_read_b128 v[180:183], v200 offset:13312
	s_waitcnt vmcnt(21) lgkmcnt(3)
	v_mfma_f32_16x16x32_f16 v[0:3], v[192:195], v[68:71], v[0:3]
	ds_read_b128 v[184:187], v200 offset:14336
	s_waitcnt vmcnt(20) lgkmcnt(3)
	v_mfma_f32_16x16x32_f16 v[0:3], v[196:199], v[72:75], v[0:3]
	ds_read_b128 v[188:191], v200 offset:15360
	s_waitcnt vmcnt(19) lgkmcnt(3)
	v_mfma_f32_16x16x32_f16 v[0:3], v[176:179], v[76:79], v[0:3]
	ds_read_b128 v[192:195], v200 offset:16384
	s_waitcnt vmcnt(18) lgkmcnt(3)
	v_mfma_f32_16x16x32_f16 v[0:3], v[180:183], v[80:83], v[0:3]
	ds_read_b128 v[196:199], v200 offset:17408
	s_waitcnt vmcnt(17) lgkmcnt(3)
	v_mfma_f32_16x16x32_f16 v[0:3], v[184:187], v[84:87], v[0:3]
	ds_read_b128 v[176:179], v200 offset:18432
	s_waitcnt vmcnt(16) lgkmcnt(3)
	v_mfma_f32_16x16x32_f16 v[0:3], v[188:191], v[88:91], v[0:3]
	ds_read_b128 v[180:183], v200 offset:19456
	s_waitcnt vmcnt(15) lgkmcnt(3)
	v_mfma_f32_16x16x32_f16 v[0:3], v[192:195], v[92:95], v[0:3]
	ds_read_b128 v[184:187], v200 offset:20480
	s_waitcnt vmcnt(14) lgkmcnt(3)
	v_mfma_f32_16x16x32_f16 v[0:3], v[196:199], v[96:99], v[0:3]
	ds_read_b128 v[188:191], v200 offset:21504
	s_waitcnt vmcnt(13) lgkmcnt(3)
	v_mfma_f32_16x16x32_f16 v[0:3], v[176:179], v[100:103], v[0:3]
	ds_read_b128 v[192:195], v200 offset:22528
	s_waitcnt vmcnt(12) lgkmcnt(3)
	v_mfma_f32_16x16x32_f16 v[0:3], v[180:183], v[104:107], v[0:3]
	ds_read_b128 v[196:199], v200 offset:23552
	s_waitcnt vmcnt(11) lgkmcnt(3)
	v_mfma_f32_16x16x32_f16 v[0:3], v[184:187], v[108:111], v[0:3]
	ds_read_b128 v[176:179], v200 offset:24576
	s_waitcnt vmcnt(10) lgkmcnt(3)
	v_mfma_f32_16x16x32_f16 v[0:3], v[188:191], v[112:115], v[0:3]
	ds_read_b128 v[180:183], v200 offset:25600
	s_waitcnt vmcnt(9) lgkmcnt(3)
	v_mfma_f32_16x16x32_f16 v[0:3], v[192:195], v[116:119], v[0:3]
	ds_read_b128 v[184:187], v200 offset:26624
	s_waitcnt vmcnt(8) lgkmcnt(3)
	v_mfma_f32_16x16x32_f16 v[0:3], v[196:199], v[120:123], v[0:3]
	ds_read_b128 v[188:191], v200 offset:27648
	s_waitcnt vmcnt(7) lgkmcnt(3)
	v_mfma_f32_16x16x32_f16 v[0:3], v[176:179], v[124:127], v[0:3]
	ds_read_b128 v[192:195], v200 offset:28672
	s_waitcnt vmcnt(6) lgkmcnt(3)
	v_mfma_f32_16x16x32_f16 v[0:3], v[180:183], v[148:151], v[0:3]
	ds_read_b128 v[196:199], v200 offset:29696
	s_waitcnt vmcnt(5) lgkmcnt(3)
	v_mfma_f32_16x16x32_f16 v[0:3], v[184:187], v[152:155], v[0:3]
	ds_read_b128 v[176:179], v200 offset:30720
	s_waitcnt vmcnt(4) lgkmcnt(3)
	v_mfma_f32_16x16x32_f16 v[0:3], v[188:191], v[156:159], v[0:3]
	ds_read_b128 v[180:183], v200 offset:31744
	s_waitcnt vmcnt(3) lgkmcnt(3)
	v_mfma_f32_16x16x32_f16 v[0:3], v[192:195], v[160:163], v[0:3]
	s_waitcnt vmcnt(2) lgkmcnt(2)
	v_mfma_f32_16x16x32_f16 v[0:3], v[196:199], v[164:167], v[0:3]
	s_waitcnt vmcnt(1) lgkmcnt(1)
	v_mfma_f32_16x16x32_f16 v[0:3], v[176:179], v[168:171], v[0:3]
	s_waitcnt vmcnt(0) lgkmcnt(0)
	v_mfma_f32_16x16x32_f16 v[0:3], v[180:183], v[172:175], v[0:3]
	s_branch .Lsk5_done

; template <int MODE>
; __device__ __forceinline__ void skinny(const Params& p, const h16* A, int lda, int row0, int nrt, const h16* Bt, int K, int nct) {
;     ...
;             const float rstd = rsqrtf(((const float*)(ws + OFF_SS1))[row] * (1.f / 1024.f) + EPS);
;             f32x4 v;
; #pragma unroll
;             for (int r = 0; r < 4; ++r) { const float a = fmaxf(acc[r] * rstd, 0.f); v[r] = a * a; }
;             *(h16x4*)((h16*)(ws + OFF_HID16) + (size_t)row * DFF + col) = pack4(v);
.Lsk5_done:
	v_lshl_add_u64 v[6:7], v[4:5], 2, s[14:15]
	global_load_dword v7, v[6:7], off
	v_lshlrev_b64 v[8:9], 13, v[4:5]
	v_or_b32_e32 v6, v12, v138
	v_lshl_add_u64 v[8:9], s[12:13], 0, v[8:9]
	v_add_u32_e32 v11, s88, v11
	v_cmp_lt_i32_e64 s[0:1], s19, v11
	s_or_b64 s[8:9], s[0:1], s[8:9]
	s_waitcnt vmcnt(0)
	v_fmamk_f32 v4, v7, 0x3a800000, v10
	v_mul_f32_e32 v7, 0x4b800000, v4
	v_cmp_gt_f32_e32 vcc, s18, v4
	s_nop 1
	v_cndmask_b32_e32 v4, v4, v7, vcc
	v_rsq_f32_e32 v4, v4
	v_ashrrev_i32_e32 v7, 31, v6
	v_lshl_add_u64 v[6:7], v[6:7], 1, v[8:9]
	v_mul_f32_e32 v8, 0x45800000, v4
	v_cndmask_b32_e32 v4, v4, v8, vcc
	v_mul_f32_e32 v0, v0, v4
	v_mul_f32_e32 v1, v1, v4
	v_mul_f32_e32 v2, v2, v4
	v_mul_f32_e32 v3, v3, v4
	v_max_f32_e32 v4, 0, v0
	v_max_f32_e32 v0, 0, v1
	v_max_f32_e32 v1, 0, v2
	v_max_f32_e32 v2, 0, v3
	v_pk_mul_f32 v[0:1], v[0:1], v[0:1]
	v_fma_mixlo_f16 v3, v4, v4, 0
	v_fma_mixlo_f16 v2, v2, v2, 0
	v_cvt_pk_f16_f32 v1, v0, v1
	v_pack_b32_f16 v0, v3, v1
	v_alignbit_b32 v1, v2, v1, 16
	global_store_dwordx2 v[6:7], v[0:1], off
	s_andn2_b64 exec, exec, s[8:9]
	s_cbranch_execnz .LBB0_490
